# folded score weights: all 12 staging loads of an item in flight at once, 128x64x128 f32 product on v_mfma_f32_32x32x2_f32 (f32 operands and accumulate) instead of packed-f32 VALU FMAs
# speedup vs baseline: 1.0029x; 1.0029x over previous
.LBB0_402:
	s_ashr_i32 s18, s7, 5
	s_bfe_u32 s30, s7, 0x10004
	s_and_b32 s31, s7, 15
	s_lshl_b32 s19, s31, 6
	s_cmp_eq_u32 s30, 0
	s_cselect_b32 s8, s85, s87
	s_cselect_b32 s0, s84, s86
	s_lshl_b32 s1, s18, 16
	s_add_u32 s44, s0, s1
	s_addc_u32 s45, s8, 0
	s_lshl_b32 s0, s18, 10
	s_lshl_b32 s1, s30, 9
	s_add_u32 s0, s0, s1
	s_lshl_b32 s1, s19, 13
	s_add_u32 s0, s0, s1
	s_add_u32 s46, s82, s0
	s_addc_u32 s47, s83, 0
	s_add_u32 s42, s26, 0xa00000
	s_addc_u32 s43, s27, 0
	v_lshrrev_b32_e32 v0, 5, v32
	v_lshlrev_b32_e32 v1, 4, v35
	v_mov_b32_e32 v2, 0x210
	v_mul_lo_u32 v3, v0, v2
	v_add_u32_e32 v28, v3, v1
	v_add_u32_e32 v29, 0x10800, v28
	v_lshlrev_b32_e32 v30, 4, v32
	v_lshl_add_u32 v31, v0, 13, v1
	v_mov_b32_e32 v16, v30
	v_add_u32_e32 v17, 0x2000, v30
	v_add_u32_e32 v18, 0x4000, v30
	v_add_u32_e32 v19, 0x6000, v30
	v_add_u32_e32 v20, 0x8000, v30
	v_add_u32_e32 v21, 0xa000, v30
	v_add_u32_e32 v22, 0xc000, v30
	v_add_u32_e32 v23, 0xe000, v30
	v_mov_b32_e32 v24, v31
	v_add_u32_e32 v25, 0x20000, v31
	v_add_u32_e32 v26, 0x40000, v31
	v_add_u32_e32 v27, 0x60000, v31
	global_load_dwordx4 v[40:43], v16, s[44:45]
	global_load_dwordx4 v[44:47], v17, s[44:45]
	global_load_dwordx4 v[48:51], v18, s[44:45]
	global_load_dwordx4 v[52:55], v19, s[44:45]
	global_load_dwordx4 v[56:59], v20, s[44:45]
	global_load_dwordx4 v[60:63], v21, s[44:45]
	global_load_dwordx4 v[64:67], v22, s[44:45]
	global_load_dwordx4 v[68:71], v23, s[44:45]
	global_load_dwordx4 v[72:75], v24, s[46:47]
	global_load_dwordx4 v[76:79], v25, s[46:47]
	global_load_dwordx4 v[80:83], v26, s[46:47]
	global_load_dwordx4 v[84:87], v27, s[46:47]
	v_bfe_u32 v0, v32, 5, 1
	v_and_b32_e32 v1, 1, v33
	v_lshrrev_b32_e32 v2, 1, v33
	v_mov_b32_e32 v3, 0x210
	v_lshl_add_u32 v4, v1, 5, v35
	v_mul_lo_u32 v4, v4, v3
	v_lshl_add_u32 v4, v0, 4, v4
	v_add_u32_e32 v34, 0x10800, v4
	v_lshl_add_u32 v5, v2, 5, v35
	v_mul_lo_u32 v6, v5, v3
	v_lshl_add_u32 v36, v0, 4, v6
	s_lshl_b32 s0, s18, 8
	s_lshl_b32 s1, s30, 7
	s_or_b32 s0, s0, s1
	v_add_u32_e32 v5, s0, v5
	s_lshl_b32 s1, s31, 5
	v_lshlrev_b32_e32 v6, 9, v5
	v_lshl_add_u32 v6, v1, 4, v6
	v_add_u32_e32 v39, s1, v6
	s_lshl_b32 s1, s19, 1
	v_lshlrev_b32_e32 v6, 11, v5
	v_lshl_add_u32 v6, v1, 6, v6
	v_lshl_add_u32 v6, v0, 3, v6
	v_add_u32_e32 v38, s1, v6
	s_lshl_b32 s1, s19, 2
	v_lshlrev_b32_e32 v6, 7, v1
	v_lshl_add_u32 v6, v0, 4, v6
	v_add_u32_e32 v8, s1, v6
	s_waitcnt vmcnt(11)
	ds_write_b128 v28, v[40:43]
	s_waitcnt vmcnt(10)
	ds_write_b128 v28, v[44:47] offset:8448
	s_waitcnt vmcnt(9)
	ds_write_b128 v28, v[48:51] offset:16896
	s_waitcnt vmcnt(8)
	ds_write_b128 v28, v[52:55] offset:25344
	s_waitcnt vmcnt(7)
	ds_write_b128 v28, v[56:59] offset:33792
	s_waitcnt vmcnt(6)
	ds_write_b128 v28, v[60:63] offset:42240
	s_waitcnt vmcnt(5)
	ds_write_b128 v28, v[64:67] offset:50688
	s_waitcnt vmcnt(4)
	ds_write_b128 v28, v[68:71] offset:59136
	s_waitcnt vmcnt(3)
	ds_write_b128 v29, v[72:75]
	s_waitcnt vmcnt(2)
	ds_write_b128 v29, v[76:79] offset:8448
	s_waitcnt vmcnt(1)
	ds_write_b128 v29, v[80:83] offset:16896
	s_waitcnt vmcnt(0)
	ds_write_b128 v29, v[84:87] offset:25344
	global_load_dwordx4 v[40:43], v8, s[78:79]
	global_load_dwordx4 v[44:47], v8, s[78:79] offset:32
	global_load_dwordx4 v[48:51], v8, s[78:79] offset:64
	global_load_dwordx4 v[52:55], v8, s[78:79] offset:96
	global_load_dwordx4 v[56:59], v8, s[80:81]
	global_load_dwordx4 v[60:63], v8, s[80:81] offset:32
	global_load_dwordx4 v[64:67], v8, s[80:81] offset:64
	global_load_dwordx4 v[68:71], v8, s[80:81] offset:96
	s_waitcnt lgkmcnt(0)
	s_barrier
	ds_read_b128 v[16:19], v34
	ds_read_b128 v[72:75], v36
	ds_read_b128 v[20:23], v34 offset:32
	ds_read_b128 v[76:79], v36 offset:32
	ds_read_b128 v[24:27], v34 offset:64
	ds_read_b128 v[80:83], v36 offset:64
	ds_read_b128 v[28:31], v34 offset:96
	ds_read_b128 v[84:87], v36 offset:96
	s_waitcnt lgkmcnt(6)
	v_mfma_f32_32x32x2_f32 v[0:15], v16, v72, 0
	v_mfma_f32_32x32x2_f32 v[0:15], v17, v73, v[0:15]
	v_mfma_f32_32x32x2_f32 v[0:15], v18, v74, v[0:15]
	v_mfma_f32_32x32x2_f32 v[0:15], v19, v75, v[0:15]
	ds_read_b128 v[16:19], v34 offset:128
	ds_read_b128 v[72:75], v36 offset:128
	s_waitcnt lgkmcnt(6)
	v_mfma_f32_32x32x2_f32 v[0:15], v20, v76, v[0:15]
	v_mfma_f32_32x32x2_f32 v[0:15], v21, v77, v[0:15]
	v_mfma_f32_32x32x2_f32 v[0:15], v22, v78, v[0:15]
	v_mfma_f32_32x32x2_f32 v[0:15], v23, v79, v[0:15]
	ds_read_b128 v[20:23], v34 offset:160
	ds_read_b128 v[76:79], v36 offset:160
	s_waitcnt lgkmcnt(6)
	v_mfma_f32_32x32x2_f32 v[0:15], v24, v80, v[0:15]
	v_mfma_f32_32x32x2_f32 v[0:15], v25, v81, v[0:15]
	v_mfma_f32_32x32x2_f32 v[0:15], v26, v82, v[0:15]
	v_mfma_f32_32x32x2_f32 v[0:15], v27, v83, v[0:15]
	ds_read_b128 v[24:27], v34 offset:192
	ds_read_b128 v[80:83], v36 offset:192
	s_waitcnt lgkmcnt(6)
	v_mfma_f32_32x32x2_f32 v[0:15], v28, v84, v[0:15]
	v_mfma_f32_32x32x2_f32 v[0:15], v29, v85, v[0:15]
	v_mfma_f32_32x32x2_f32 v[0:15], v30, v86, v[0:15]
	v_mfma_f32_32x32x2_f32 v[0:15], v31, v87, v[0:15]
	ds_read_b128 v[28:31], v34 offset:224
	ds_read_b128 v[84:87], v36 offset:224
	s_waitcnt lgkmcnt(6)
	v_mfma_f32_32x32x2_f32 v[0:15], v16, v72, v[0:15]
	v_mfma_f32_32x32x2_f32 v[0:15], v17, v73, v[0:15]
	v_mfma_f32_32x32x2_f32 v[0:15], v18, v74, v[0:15]
	v_mfma_f32_32x32x2_f32 v[0:15], v19, v75, v[0:15]
	ds_read_b128 v[16:19], v34 offset:256
	ds_read_b128 v[72:75], v36 offset:256
	s_waitcnt lgkmcnt(6)
	v_mfma_f32_32x32x2_f32 v[0:15], v20, v76, v[0:15]
	v_mfma_f32_32x32x2_f32 v[0:15], v21, v77, v[0:15]
	v_mfma_f32_32x32x2_f32 v[0:15], v22, v78, v[0:15]
	v_mfma_f32_32x32x2_f32 v[0:15], v23, v79, v[0:15]
	ds_read_b128 v[20:23], v34 offset:288
	ds_read_b128 v[76:79], v36 offset:288
	s_waitcnt lgkmcnt(6)
	v_mfma_f32_32x32x2_f32 v[0:15], v24, v80, v[0:15]
	v_mfma_f32_32x32x2_f32 v[0:15], v25, v81, v[0:15]
	v_mfma_f32_32x32x2_f32 v[0:15], v26, v82, v[0:15]
	v_mfma_f32_32x32x2_f32 v[0:15], v27, v83, v[0:15]
	ds_read_b128 v[24:27], v34 offset:320
	ds_read_b128 v[80:83], v36 offset:320
	s_waitcnt lgkmcnt(6)
	v_mfma_f32_32x32x2_f32 v[0:15], v28, v84, v[0:15]
	v_mfma_f32_32x32x2_f32 v[0:15], v29, v85, v[0:15]
	v_mfma_f32_32x32x2_f32 v[0:15], v30, v86, v[0:15]
	v_mfma_f32_32x32x2_f32 v[0:15], v31, v87, v[0:15]
	ds_read_b128 v[28:31], v34 offset:352
	ds_read_b128 v[84:87], v36 offset:352
	s_waitcnt lgkmcnt(6)
	v_mfma_f32_32x32x2_f32 v[0:15], v16, v72, v[0:15]
	v_mfma_f32_32x32x2_f32 v[0:15], v17, v73, v[0:15]
	v_mfma_f32_32x32x2_f32 v[0:15], v18, v74, v[0:15]
	v_mfma_f32_32x32x2_f32 v[0:15], v19, v75, v[0:15]
	ds_read_b128 v[16:19], v34 offset:384
	ds_read_b128 v[72:75], v36 offset:384
	s_waitcnt lgkmcnt(6)
	v_mfma_f32_32x32x2_f32 v[0:15], v20, v76, v[0:15]
	v_mfma_f32_32x32x2_f32 v[0:15], v21, v77, v[0:15]
	v_mfma_f32_32x32x2_f32 v[0:15], v22, v78, v[0:15]
	v_mfma_f32_32x32x2_f32 v[0:15], v23, v79, v[0:15]
	ds_read_b128 v[20:23], v34 offset:416
	ds_read_b128 v[76:79], v36 offset:416
	s_waitcnt lgkmcnt(6)
	v_mfma_f32_32x32x2_f32 v[0:15], v24, v80, v[0:15]
	v_mfma_f32_32x32x2_f32 v[0:15], v25, v81, v[0:15]
	v_mfma_f32_32x32x2_f32 v[0:15], v26, v82, v[0:15]
	v_mfma_f32_32x32x2_f32 v[0:15], v27, v83, v[0:15]
	ds_read_b128 v[24:27], v34 offset:448
	ds_read_b128 v[80:83], v36 offset:448
	s_waitcnt lgkmcnt(6)
	v_mfma_f32_32x32x2_f32 v[0:15], v28, v84, v[0:15]
	v_mfma_f32_32x32x2_f32 v[0:15], v29, v85, v[0:15]
	v_mfma_f32_32x32x2_f32 v[0:15], v30, v86, v[0:15]
	v_mfma_f32_32x32x2_f32 v[0:15], v31, v87, v[0:15]
	ds_read_b128 v[28:31], v34 offset:480
	ds_read_b128 v[84:87], v36 offset:480
	s_waitcnt lgkmcnt(6)
	v_mfma_f32_32x32x2_f32 v[0:15], v16, v72, v[0:15]
	v_mfma_f32_32x32x2_f32 v[0:15], v17, v73, v[0:15]
	v_mfma_f32_32x32x2_f32 v[0:15], v18, v74, v[0:15]
	v_mfma_f32_32x32x2_f32 v[0:15], v19, v75, v[0:15]
	s_waitcnt lgkmcnt(4)
	v_mfma_f32_32x32x2_f32 v[0:15], v20, v76, v[0:15]
	v_mfma_f32_32x32x2_f32 v[0:15], v21, v77, v[0:15]
	v_mfma_f32_32x32x2_f32 v[0:15], v22, v78, v[0:15]
	v_mfma_f32_32x32x2_f32 v[0:15], v23, v79, v[0:15]
	s_waitcnt lgkmcnt(2)
	v_mfma_f32_32x32x2_f32 v[0:15], v24, v80, v[0:15]
	v_mfma_f32_32x32x2_f32 v[0:15], v25, v81, v[0:15]
	v_mfma_f32_32x32x2_f32 v[0:15], v26, v82, v[0:15]
	v_mfma_f32_32x32x2_f32 v[0:15], v27, v83, v[0:15]
	s_waitcnt lgkmcnt(0)
	v_mfma_f32_32x32x2_f32 v[0:15], v28, v84, v[0:15]
	v_mfma_f32_32x32x2_f32 v[0:15], v29, v85, v[0:15]
	v_mfma_f32_32x32x2_f32 v[0:15], v30, v86, v[0:15]
	v_mfma_f32_32x32x2_f32 v[0:15], v31, v87, v[0:15]
	s_nop 15
	s_nop 7
	s_waitcnt vmcnt(0)
	v_mul_f32_e32 v24, v1, v57
	v_fmac_f32_e32 v24, v0, v56
	v_mul_f32_e32 v25, v3, v59
	v_fmac_f32_e32 v25, v2, v58
	v_add_f32_e32 v84, v24, v25
	v_pk_mul_f32 v[0:1], v[0:1], v[40:41]
	v_pk_mul_f32 v[2:3], v[2:3], v[42:43]
	v_cvt_pk_bf16_f32 v72, v0, v1
	v_cvt_pk_bf16_f32 v73, v2, v3
	v_lshlrev_b32_e32 v26, 16, v72
	v_and_b32_e32 v27, 0xffff0000, v72
	v_lshlrev_b32_e32 v28, 16, v73
	v_and_b32_e32 v29, 0xffff0000, v73
	v_add_f32_e32 v26, v26, v27
	v_add_f32_e32 v28, v28, v29
	v_add_f32_e32 v80, v26, v28
	ds_bpermute_b32 v16, v37, v80
	ds_bpermute_b32 v20, v37, v84
	global_store_dwordx2 v38, v[72:73], s[42:43]
	v_mul_f32_e32 v24, v5, v61
	v_fmac_f32_e32 v24, v4, v60
	v_mul_f32_e32 v25, v7, v63
	v_fmac_f32_e32 v25, v6, v62
	v_add_f32_e32 v85, v24, v25
	v_pk_mul_f32 v[4:5], v[4:5], v[44:45]
	v_pk_mul_f32 v[6:7], v[6:7], v[46:47]
	v_cvt_pk_bf16_f32 v74, v4, v5
	v_cvt_pk_bf16_f32 v75, v6, v7
	v_lshlrev_b32_e32 v26, 16, v74
	v_and_b32_e32 v27, 0xffff0000, v74
	v_lshlrev_b32_e32 v28, 16, v75
	v_and_b32_e32 v29, 0xffff0000, v75
	v_add_f32_e32 v26, v26, v27
	v_add_f32_e32 v28, v28, v29
	v_add_f32_e32 v81, v26, v28
	ds_bpermute_b32 v17, v37, v81
	ds_bpermute_b32 v21, v37, v85
	global_store_dwordx2 v38, v[74:75], s[42:43] offset:16
	v_mul_f32_e32 v24, v9, v65
	v_fmac_f32_e32 v24, v8, v64
	v_mul_f32_e32 v25, v11, v67
	v_fmac_f32_e32 v25, v10, v66
	v_add_f32_e32 v86, v24, v25
	v_pk_mul_f32 v[8:9], v[8:9], v[48:49]
	v_pk_mul_f32 v[10:11], v[10:11], v[50:51]
	v_cvt_pk_bf16_f32 v76, v8, v9
	v_cvt_pk_bf16_f32 v77, v10, v11
	v_lshlrev_b32_e32 v26, 16, v76
	v_and_b32_e32 v27, 0xffff0000, v76
	v_lshlrev_b32_e32 v28, 16, v77
	v_and_b32_e32 v29, 0xffff0000, v77
	v_add_f32_e32 v26, v26, v27
	v_add_f32_e32 v28, v28, v29
	v_add_f32_e32 v82, v26, v28
	ds_bpermute_b32 v18, v37, v82
	ds_bpermute_b32 v22, v37, v86
	global_store_dwordx2 v38, v[76:77], s[42:43] offset:32
	v_mul_f32_e32 v24, v13, v69
	v_fmac_f32_e32 v24, v12, v68
	v_mul_f32_e32 v25, v15, v71
	v_fmac_f32_e32 v25, v14, v70
	v_add_f32_e32 v87, v24, v25
	v_pk_mul_f32 v[12:13], v[12:13], v[52:53]
	v_pk_mul_f32 v[14:15], v[14:15], v[54:55]
	v_cvt_pk_bf16_f32 v78, v12, v13
	v_cvt_pk_bf16_f32 v79, v14, v15
	v_lshlrev_b32_e32 v26, 16, v78
	v_and_b32_e32 v27, 0xffff0000, v78
	v_lshlrev_b32_e32 v28, 16, v79
	v_and_b32_e32 v29, 0xffff0000, v79
	v_add_f32_e32 v26, v26, v27
	v_add_f32_e32 v28, v28, v29
	v_add_f32_e32 v83, v26, v28
	ds_bpermute_b32 v19, v37, v83
	ds_bpermute_b32 v23, v37, v87
	global_store_dwordx2 v38, v[78:79], s[42:43] offset:48
	s_waitcnt lgkmcnt(0)
	v_add_f32_e32 v80, v80, v16
	v_add_f32_e32 v84, v84, v20
	v_add_f32_e32 v81, v81, v17
	v_add_f32_e32 v85, v85, v21
	v_add_f32_e32 v82, v82, v18
	v_add_f32_e32 v86, v86, v22
	v_add_f32_e32 v83, v83, v19
	v_add_f32_e32 v87, v87, v23
	s_mov_b32 exec_hi, 0
	global_store_dword v39, v80, s[12:13]
	global_store_dword v39, v84, s[14:15]
	global_store_dword v39, v81, s[12:13] offset:4
	global_store_dword v39, v85, s[14:15] offset:4
	global_store_dword v39, v82, s[12:13] offset:8
	global_store_dword v39, v86, s[14:15] offset:8
	global_store_dword v39, v83, s[12:13] offset:12
	global_store_dword v39, v87, s[14:15] offset:12
	s_mov_b64 exec, -1
	s_add_i32 s7, s7, s48
	s_cmpk_gt_i32 s7, 0xff
	s_barrier
	s_cbranch_scc0 .LBB0_402
	s_branch .LBB0_418
	s_nop 0
	s_nop 0
	s_nop 0
	s_nop 0
	s_nop 0
	s_nop 0
	s_nop 0
	s_nop 0
	s_nop 0
	s_nop 0
	s_nop 0
	s_nop 0
	s_nop 0
